# prep LoRA inner loop hand-written: accumulators paired over a lane's two channels so LDS quads feed v_pk_fma_f32 directly (no register shuffles), LDS reads 3 groups ahead, weight loads one step ahead;
# speedup vs baseline: 1.0322x; 1.0306x over previous
; DI void prep_phase(const Params& p, int l, char* smem, const bool dry = false) {
;     ...
;       float accw[2][8], acca[2][8];
; #pragma unroll
;       for (int ch = 0; ch < 2; ch++) {
;         const int c = tid + 256 * ch;
;         const float bw = p.w0[l * 512 + c], ba = p.a0[l * 512 + c];
; #pragma unroll
;         for (int tk = 0; tk < 8; tk++) { accw[ch][tk] = bw; acca[ch][tk] = ba; }
;       }
;       for (int i4 = 0; i4 < 16; i4++) {
;         float4 twv[8], tav[8];
; #pragma unroll
;         for (int tk = 0; tk < 8; tk++) {
;           twv[tk] = *(const float4*)(tw + tk * 64 + i4 * 4);
;           tav[tk] = *(const float4*)(ta + tk * 64 + i4 * 4);
;         }
; #pragma unroll
;         for (int ii = 0; ii < 4; ii++) {
;           const int i = i4 * 4 + ii;
; #pragma unroll
;           for (int ch = 0; ch < 2; ch++) {
;             const int c = tid + 256 * ch;
;             const float wv = w2[i * 512 + c], av = a2[i * 512 + c];
; #pragma unroll
;             for (int tk = 0; tk < 8; tk++) {
;               const float x = ii == 0 ? twv[tk].x : ii == 1 ? twv[tk].y : ii == 2 ? twv[tk].z : twv[tk].w;
;               const float y = ii == 0 ? tav[tk].x : ii == 1 ? tav[tk].y : ii == 2 ? tav[tk].z : tav[tk].w;
;               accw[ch][tk] += x * wv;
;               acca[ch][tk] += y * av;
;             }
;           }
;         }
.LBB0_1175:
	s_or_b64 exec, exec, s[14:15]
	s_waitcnt lgkmcnt(0)
	s_barrier
	global_load_dword v66, v[18:19], off
	global_load_dword v50, v[18:19], off offset:1024
	global_load_dword v68, v[16:17], off
	global_load_dword v52, v[16:17], off offset:1024
	s_waitcnt vmcnt(0)
	v_mov_b32_e32 v124, v68
	v_mov_b32_e32 v125, v52
	v_mov_b32_e32 v126, v66
	v_mov_b32_e32 v127, v50
	v_mov_b32_e32 v102, 0xea00
	v_lshlrev_b32_e32 v103, 2, v4
	v_add_u32_e32 v104, 0x1000, v103
	global_load_dword v224, v103, s[16:17] offset:0
	global_load_dword v225, v103, s[16:17] offset:1024
	global_load_dword v232, v103, s[24:25] offset:0
	global_load_dword v233, v103, s[24:25] offset:1024
	global_load_dword v226, v103, s[16:17] offset:2048
	global_load_dword v227, v103, s[16:17] offset:3072
	global_load_dword v234, v103, s[24:25] offset:2048
	global_load_dword v235, v103, s[24:25] offset:3072
	global_load_dword v228, v104, s[16:17] offset:0
	global_load_dword v229, v104, s[16:17] offset:1024
	global_load_dword v236, v104, s[24:25] offset:0
	global_load_dword v237, v104, s[24:25] offset:1024
	global_load_dword v230, v104, s[16:17] offset:2048
	global_load_dword v231, v104, s[16:17] offset:3072
	global_load_dword v238, v104, s[24:25] offset:2048
	global_load_dword v239, v104, s[24:25] offset:3072
	v_add_u32_e32 v103, 0x2000, v103
	v_add_u32_e32 v104, 0x2000, v104
	ds_read_b128 v[70:73], v102 offset:0
	ds_read_b128 v[74:77], v102 offset:256
	ds_read_b128 v[78:81], v102 offset:2048
	ds_read_b128 v[82:85], v102 offset:2304
	ds_read_b128 v[86:89], v102 offset:512
	ds_read_b128 v[90:93], v102 offset:768
	ds_read_b128 v[94:97], v102 offset:2560
	ds_read_b128 v[98:101], v102 offset:2816
	ds_read_b128 v[108:111], v102 offset:1024
	ds_read_b128 v[112:115], v102 offset:1280
	ds_read_b128 v[116:119], v102 offset:3072
	ds_read_b128 v[120:123], v102 offset:3328
	v_mov_b32_e32 v38, v124
	v_mov_b32_e32 v39, v125
	v_mov_b32_e32 v54, v126
	v_mov_b32_e32 v55, v127
	v_mov_b32_e32 v40, v124
	v_mov_b32_e32 v41, v125
	v_mov_b32_e32 v56, v126
	v_mov_b32_e32 v57, v127
	v_mov_b32_e32 v42, v124
	v_mov_b32_e32 v43, v125
	v_mov_b32_e32 v58, v126
	v_mov_b32_e32 v59, v127
	v_mov_b32_e32 v44, v124
	v_mov_b32_e32 v45, v125
	v_mov_b32_e32 v60, v126
	v_mov_b32_e32 v61, v127
	v_mov_b32_e32 v46, v124
	v_mov_b32_e32 v47, v125
	v_mov_b32_e32 v62, v126
	v_mov_b32_e32 v63, v127
	v_mov_b32_e32 v48, v124
	v_mov_b32_e32 v49, v125
	v_mov_b32_e32 v64, v126
	v_mov_b32_e32 v65, v127
	v_mov_b32_e32 v50, v124
	v_mov_b32_e32 v51, v125
	v_mov_b32_e32 v66, v126
	v_mov_b32_e32 v67, v127
	v_mov_b32_e32 v52, v124
	v_mov_b32_e32 v53, v125
	v_mov_b32_e32 v68, v126
	v_mov_b32_e32 v69, v127
	s_mov_b32 s14, 0
.Llora_loop:
	global_load_dword v240, v103, s[16:17] offset:0
	global_load_dword v241, v103, s[16:17] offset:1024
	global_load_dword v152, v103, s[24:25] offset:0
	global_load_dword v153, v103, s[24:25] offset:1024
	global_load_dword v242, v103, s[16:17] offset:2048
	global_load_dword v243, v103, s[16:17] offset:3072
	global_load_dword v154, v103, s[24:25] offset:2048
	global_load_dword v155, v103, s[24:25] offset:3072
	global_load_dword v244, v104, s[16:17] offset:0
	global_load_dword v245, v104, s[16:17] offset:1024
	global_load_dword v156, v104, s[24:25] offset:0
	global_load_dword v157, v104, s[24:25] offset:1024
	global_load_dword v246, v104, s[16:17] offset:2048
	global_load_dword v247, v104, s[16:17] offset:3072
	global_load_dword v158, v104, s[24:25] offset:2048
	global_load_dword v159, v104, s[24:25] offset:3072
	v_add_u32_e32 v103, 0x2000, v103
	v_add_u32_e32 v104, 0x2000, v104
	s_waitcnt vmcnt(16)
	s_waitcnt lgkmcnt(8)
	ds_read_b128 v[136:139], v102 offset:1536
	ds_read_b128 v[140:143], v102 offset:1792
	ds_read_b128 v[144:147], v102 offset:3584
	ds_read_b128 v[148:151], v102 offset:3840
	v_pk_fma_f32 v[38:39], v[70:71], v[224:225], v[38:39] op_sel_hi:[0,1,1]
	v_pk_fma_f32 v[40:41], v[74:75], v[224:225], v[40:41] op_sel_hi:[0,1,1]
	v_pk_fma_f32 v[54:55], v[78:79], v[232:233], v[54:55] op_sel_hi:[0,1,1]
	v_pk_fma_f32 v[56:57], v[82:83], v[232:233], v[56:57] op_sel_hi:[0,1,1]
	v_pk_fma_f32 v[38:39], v[70:71], v[226:227], v[38:39] op_sel:[1,0,0] op_sel_hi:[1,1,1]
	v_pk_fma_f32 v[40:41], v[74:75], v[226:227], v[40:41] op_sel:[1,0,0] op_sel_hi:[1,1,1]
	v_pk_fma_f32 v[54:55], v[78:79], v[234:235], v[54:55] op_sel:[1,0,0] op_sel_hi:[1,1,1]
	v_pk_fma_f32 v[56:57], v[82:83], v[234:235], v[56:57] op_sel:[1,0,0] op_sel_hi:[1,1,1]
	v_pk_fma_f32 v[38:39], v[72:73], v[228:229], v[38:39] op_sel_hi:[0,1,1]
	v_pk_fma_f32 v[40:41], v[76:77], v[228:229], v[40:41] op_sel_hi:[0,1,1]
	v_pk_fma_f32 v[54:55], v[80:81], v[236:237], v[54:55] op_sel_hi:[0,1,1]
	v_pk_fma_f32 v[56:57], v[84:85], v[236:237], v[56:57] op_sel_hi:[0,1,1]
	v_pk_fma_f32 v[38:39], v[72:73], v[230:231], v[38:39] op_sel:[1,0,0] op_sel_hi:[1,1,1]
	v_pk_fma_f32 v[40:41], v[76:77], v[230:231], v[40:41] op_sel:[1,0,0] op_sel_hi:[1,1,1]
	v_pk_fma_f32 v[54:55], v[80:81], v[238:239], v[54:55] op_sel:[1,0,0] op_sel_hi:[1,1,1]
	v_pk_fma_f32 v[56:57], v[84:85], v[238:239], v[56:57] op_sel:[1,0,0] op_sel_hi:[1,1,1]
	s_waitcnt lgkmcnt(8)
; DI void prep_phase(const Params& p, int l, char* smem, const bool dry = false) {
;     ...
;       for (int i4 = 0; i4 < 16; i4++) {
;         float4 twv[8], tav[8];
; #pragma unroll
;         for (int tk = 0; tk < 8; tk++) {
;           twv[tk] = *(const float4*)(tw + tk * 64 + i4 * 4);
;           tav[tk] = *(const float4*)(ta + tk * 64 + i4 * 4);
;         }
; #pragma unroll
;         for (int ii = 0; ii < 4; ii++) {
;           const int i = i4 * 4 + ii;
; #pragma unroll
;           for (int ch = 0; ch < 2; ch++) {
;             const int c = tid + 256 * ch;
;             const float wv = w2[i * 512 + c], av = a2[i * 512 + c];
; #pragma unroll
;             for (int tk = 0; tk < 8; tk++) {
;               const float x = ii == 0 ? twv[tk].x : ii == 1 ? twv[tk].y : ii == 2 ? twv[tk].z : twv[tk].w;
;               const float y = ii == 0 ? tav[tk].x : ii == 1 ? tav[tk].y : ii == 2 ? tav[tk].z : tav[tk].w;
;               accw[ch][tk] += x * wv;
;               acca[ch][tk] += y * av;
;             }
;           }
	ds_read_b128 v[70:73], v102 offset:16
	ds_read_b128 v[74:77], v102 offset:272
	ds_read_b128 v[78:81], v102 offset:2064
	ds_read_b128 v[82:85], v102 offset:2320
	v_pk_fma_f32 v[42:43], v[86:87], v[224:225], v[42:43] op_sel_hi:[0,1,1]
	v_pk_fma_f32 v[44:45], v[90:91], v[224:225], v[44:45] op_sel_hi:[0,1,1]
	v_pk_fma_f32 v[58:59], v[94:95], v[232:233], v[58:59] op_sel_hi:[0,1,1]
	v_pk_fma_f32 v[60:61], v[98:99], v[232:233], v[60:61] op_sel_hi:[0,1,1]
	v_pk_fma_f32 v[42:43], v[86:87], v[226:227], v[42:43] op_sel:[1,0,0] op_sel_hi:[1,1,1]
	v_pk_fma_f32 v[44:45], v[90:91], v[226:227], v[44:45] op_sel:[1,0,0] op_sel_hi:[1,1,1]
	v_pk_fma_f32 v[58:59], v[94:95], v[234:235], v[58:59] op_sel:[1,0,0] op_sel_hi:[1,1,1]
	v_pk_fma_f32 v[60:61], v[98:99], v[234:235], v[60:61] op_sel:[1,0,0] op_sel_hi:[1,1,1]
	v_pk_fma_f32 v[42:43], v[88:89], v[228:229], v[42:43] op_sel_hi:[0,1,1]
	v_pk_fma_f32 v[44:45], v[92:93], v[228:229], v[44:45] op_sel_hi:[0,1,1]
	v_pk_fma_f32 v[58:59], v[96:97], v[236:237], v[58:59] op_sel_hi:[0,1,1]
	v_pk_fma_f32 v[60:61], v[100:101], v[236:237], v[60:61] op_sel_hi:[0,1,1]
	v_pk_fma_f32 v[42:43], v[88:89], v[230:231], v[42:43] op_sel:[1,0,0] op_sel_hi:[1,1,1]
	v_pk_fma_f32 v[44:45], v[92:93], v[230:231], v[44:45] op_sel:[1,0,0] op_sel_hi:[1,1,1]
	v_pk_fma_f32 v[58:59], v[96:97], v[238:239], v[58:59] op_sel:[1,0,0] op_sel_hi:[1,1,1]
	v_pk_fma_f32 v[60:61], v[100:101], v[238:239], v[60:61] op_sel:[1,0,0] op_sel_hi:[1,1,1]
	s_waitcnt lgkmcnt(8)
	ds_read_b128 v[86:89], v102 offset:528
	ds_read_b128 v[90:93], v102 offset:784
	ds_read_b128 v[94:97], v102 offset:2576
	ds_read_b128 v[98:101], v102 offset:2832
	v_pk_fma_f32 v[46:47], v[108:109], v[224:225], v[46:47] op_sel_hi:[0,1,1]
	v_pk_fma_f32 v[48:49], v[112:113], v[224:225], v[48:49] op_sel_hi:[0,1,1]
	v_pk_fma_f32 v[62:63], v[116:117], v[232:233], v[62:63] op_sel_hi:[0,1,1]
	v_pk_fma_f32 v[64:65], v[120:121], v[232:233], v[64:65] op_sel_hi:[0,1,1]
	v_pk_fma_f32 v[46:47], v[108:109], v[226:227], v[46:47] op_sel:[1,0,0] op_sel_hi:[1,1,1]
	v_pk_fma_f32 v[48:49], v[112:113], v[226:227], v[48:49] op_sel:[1,0,0] op_sel_hi:[1,1,1]
	v_pk_fma_f32 v[62:63], v[116:117], v[234:235], v[62:63] op_sel:[1,0,0] op_sel_hi:[1,1,1]
	v_pk_fma_f32 v[64:65], v[120:121], v[234:235], v[64:65] op_sel:[1,0,0] op_sel_hi:[1,1,1]
	v_pk_fma_f32 v[46:47], v[110:111], v[228:229], v[46:47] op_sel_hi:[0,1,1]
	v_pk_fma_f32 v[48:49], v[114:115], v[228:229], v[48:49] op_sel_hi:[0,1,1]
	v_pk_fma_f32 v[62:63], v[118:119], v[236:237], v[62:63] op_sel_hi:[0,1,1]
	v_pk_fma_f32 v[64:65], v[122:123], v[236:237], v[64:65] op_sel_hi:[0,1,1]
	v_pk_fma_f32 v[46:47], v[110:111], v[230:231], v[46:47] op_sel:[1,0,0] op_sel_hi:[1,1,1]
	v_pk_fma_f32 v[48:49], v[114:115], v[230:231], v[48:49] op_sel:[1,0,0] op_sel_hi:[1,1,1]
	v_pk_fma_f32 v[62:63], v[118:119], v[238:239], v[62:63] op_sel:[1,0,0] op_sel_hi:[1,1,1]
	v_pk_fma_f32 v[64:65], v[122:123], v[238:239], v[64:65] op_sel:[1,0,0] op_sel_hi:[1,1,1]
	s_waitcnt lgkmcnt(8)
	ds_read_b128 v[108:111], v102 offset:1040
	ds_read_b128 v[112:115], v102 offset:1296
	ds_read_b128 v[116:119], v102 offset:3088
	ds_read_b128 v[120:123], v102 offset:3344
	v_pk_fma_f32 v[50:51], v[136:137], v[224:225], v[50:51] op_sel_hi:[0,1,1]
	v_pk_fma_f32 v[52:53], v[140:141], v[224:225], v[52:53] op_sel_hi:[0,1,1]
	v_pk_fma_f32 v[66:67], v[144:145], v[232:233], v[66:67] op_sel_hi:[0,1,1]
	v_pk_fma_f32 v[68:69], v[148:149], v[232:233], v[68:69] op_sel_hi:[0,1,1]
	v_pk_fma_f32 v[50:51], v[136:137], v[226:227], v[50:51] op_sel:[1,0,0] op_sel_hi:[1,1,1]
	v_pk_fma_f32 v[52:53], v[140:141], v[226:227], v[52:53] op_sel:[1,0,0] op_sel_hi:[1,1,1]
	v_pk_fma_f32 v[66:67], v[144:145], v[234:235], v[66:67] op_sel:[1,0,0] op_sel_hi:[1,1,1]
	v_pk_fma_f32 v[68:69], v[148:149], v[234:235], v[68:69] op_sel:[1,0,0] op_sel_hi:[1,1,1]
	v_pk_fma_f32 v[50:51], v[138:139], v[228:229], v[50:51] op_sel_hi:[0,1,1]
	v_pk_fma_f32 v[52:53], v[142:143], v[228:229], v[52:53] op_sel_hi:[0,1,1]
	v_pk_fma_f32 v[66:67], v[146:147], v[236:237], v[66:67] op_sel_hi:[0,1,1]
	v_pk_fma_f32 v[68:69], v[150:151], v[236:237], v[68:69] op_sel_hi:[0,1,1]
	v_pk_fma_f32 v[50:51], v[138:139], v[230:231], v[50:51] op_sel:[1,0,0] op_sel_hi:[1,1,1]
	v_pk_fma_f32 v[52:53], v[142:143], v[230:231], v[52:53] op_sel:[1,0,0] op_sel_hi:[1,1,1]
	v_pk_fma_f32 v[66:67], v[146:147], v[238:239], v[66:67] op_sel:[1,0,0] op_sel_hi:[1,1,1]
	v_pk_fma_f32 v[68:69], v[150:151], v[238:239], v[68:69] op_sel:[1,0,0] op_sel_hi:[1,1,1]
	s_cmp_eq_u32 s14, 7
	s_cbranch_scc1 .Llora_last
	global_load_dword v224, v103, s[16:17] offset:0
	global_load_dword v225, v103, s[16:17] offset:1024
	global_load_dword v232, v103, s[24:25] offset:0
	global_load_dword v233, v103, s[24:25] offset:1024
	global_load_dword v226, v103, s[16:17] offset:2048
	global_load_dword v227, v103, s[16:17] offset:3072
	global_load_dword v234, v103, s[24:25] offset:2048
	global_load_dword v235, v103, s[24:25] offset:3072
	global_load_dword v228, v104, s[16:17] offset:0
	global_load_dword v229, v104, s[16:17] offset:1024
	global_load_dword v236, v104, s[24:25] offset:0
	global_load_dword v237, v104, s[24:25] offset:1024
	global_load_dword v230, v104, s[16:17] offset:2048
	global_load_dword v231, v104, s[16:17] offset:3072
	global_load_dword v238, v104, s[24:25] offset:2048
	global_load_dword v239, v104, s[24:25] offset:3072
	v_add_u32_e32 v103, 0x2000, v103
	v_add_u32_e32 v104, 0x2000, v104
	s_waitcnt vmcnt(16)
	s_branch .Llora_b

; DI void prep_phase(const Params& p, int l, char* smem, const bool dry = false) {
;     ...
;       for (int i4 = 0; i4 < 16; i4++) {
;         float4 twv[8], tav[8];
; #pragma unroll
;         for (int tk = 0; tk < 8; tk++) {
;           twv[tk] = *(const float4*)(tw + tk * 64 + i4 * 4);
;           tav[tk] = *(const float4*)(ta + tk * 64 + i4 * 4);
;         }
; #pragma unroll
;         for (int ii = 0; ii < 4; ii++) {
;           const int i = i4 * 4 + ii;
; #pragma unroll
;           for (int ch = 0; ch < 2; ch++) {
;             const int c = tid + 256 * ch;
;             const float wv = w2[i * 512 + c], av = a2[i * 512 + c];
; #pragma unroll
;             for (int tk = 0; tk < 8; tk++) {
;               const float x = ii == 0 ? twv[tk].x : ii == 1 ? twv[tk].y : ii == 2 ? twv[tk].z : twv[tk].w;
;               const float y = ii == 0 ? tav[tk].x : ii == 1 ? tav[tk].y : ii == 2 ? tav[tk].z : tav[tk].w;
;               accw[ch][tk] += x * wv;
;               acca[ch][tk] += y * av;
;             }
;           }
.Llora_b:
	s_waitcnt lgkmcnt(8)
	ds_read_b128 v[136:139], v102 offset:1552
	ds_read_b128 v[140:143], v102 offset:1808
	ds_read_b128 v[144:147], v102 offset:3600
	ds_read_b128 v[148:151], v102 offset:3856
	v_pk_fma_f32 v[38:39], v[70:71], v[240:241], v[38:39] op_sel_hi:[0,1,1]
	v_pk_fma_f32 v[40:41], v[74:75], v[240:241], v[40:41] op_sel_hi:[0,1,1]
	v_pk_fma_f32 v[54:55], v[78:79], v[152:153], v[54:55] op_sel_hi:[0,1,1]
	v_pk_fma_f32 v[56:57], v[82:83], v[152:153], v[56:57] op_sel_hi:[0,1,1]
	v_pk_fma_f32 v[38:39], v[70:71], v[242:243], v[38:39] op_sel:[1,0,0] op_sel_hi:[1,1,1]
	v_pk_fma_f32 v[40:41], v[74:75], v[242:243], v[40:41] op_sel:[1,0,0] op_sel_hi:[1,1,1]
	v_pk_fma_f32 v[54:55], v[78:79], v[154:155], v[54:55] op_sel:[1,0,0] op_sel_hi:[1,1,1]
	v_pk_fma_f32 v[56:57], v[82:83], v[154:155], v[56:57] op_sel:[1,0,0] op_sel_hi:[1,1,1]
	v_pk_fma_f32 v[38:39], v[72:73], v[244:245], v[38:39] op_sel_hi:[0,1,1]
	v_pk_fma_f32 v[40:41], v[76:77], v[244:245], v[40:41] op_sel_hi:[0,1,1]
	v_pk_fma_f32 v[54:55], v[80:81], v[156:157], v[54:55] op_sel_hi:[0,1,1]
	v_pk_fma_f32 v[56:57], v[84:85], v[156:157], v[56:57] op_sel_hi:[0,1,1]
	v_pk_fma_f32 v[38:39], v[72:73], v[246:247], v[38:39] op_sel:[1,0,0] op_sel_hi:[1,1,1]
	v_pk_fma_f32 v[40:41], v[76:77], v[246:247], v[40:41] op_sel:[1,0,0] op_sel_hi:[1,1,1]
	v_pk_fma_f32 v[54:55], v[80:81], v[158:159], v[54:55] op_sel:[1,0,0] op_sel_hi:[1,1,1]
	v_pk_fma_f32 v[56:57], v[84:85], v[158:159], v[56:57] op_sel:[1,0,0] op_sel_hi:[1,1,1]
	s_waitcnt lgkmcnt(8)
	ds_read_b128 v[70:73], v102 offset:32
	ds_read_b128 v[74:77], v102 offset:288
	ds_read_b128 v[78:81], v102 offset:2080
	ds_read_b128 v[82:85], v102 offset:2336
	v_pk_fma_f32 v[42:43], v[86:87], v[240:241], v[42:43] op_sel_hi:[0,1,1]
	v_pk_fma_f32 v[44:45], v[90:91], v[240:241], v[44:45] op_sel_hi:[0,1,1]
	v_pk_fma_f32 v[58:59], v[94:95], v[152:153], v[58:59] op_sel_hi:[0,1,1]
	v_pk_fma_f32 v[60:61], v[98:99], v[152:153], v[60:61] op_sel_hi:[0,1,1]
	v_pk_fma_f32 v[42:43], v[86:87], v[242:243], v[42:43] op_sel:[1,0,0] op_sel_hi:[1,1,1]
	v_pk_fma_f32 v[44:45], v[90:91], v[242:243], v[44:45] op_sel:[1,0,0] op_sel_hi:[1,1,1]
	v_pk_fma_f32 v[58:59], v[94:95], v[154:155], v[58:59] op_sel:[1,0,0] op_sel_hi:[1,1,1]
	v_pk_fma_f32 v[60:61], v[98:99], v[154:155], v[60:61] op_sel:[1,0,0] op_sel_hi:[1,1,1]
	v_pk_fma_f32 v[42:43], v[88:89], v[244:245], v[42:43] op_sel_hi:[0,1,1]
	v_pk_fma_f32 v[44:45], v[92:93], v[244:245], v[44:45] op_sel_hi:[0,1,1]
	v_pk_fma_f32 v[58:59], v[96:97], v[156:157], v[58:59] op_sel_hi:[0,1,1]
	v_pk_fma_f32 v[60:61], v[100:101], v[156:157], v[60:61] op_sel_hi:[0,1,1]
	v_pk_fma_f32 v[42:43], v[88:89], v[246:247], v[42:43] op_sel:[1,0,0] op_sel_hi:[1,1,1]
	v_pk_fma_f32 v[44:45], v[92:93], v[246:247], v[44:45] op_sel:[1,0,0] op_sel_hi:[1,1,1]
	v_pk_fma_f32 v[58:59], v[96:97], v[158:159], v[58:59] op_sel:[1,0,0] op_sel_hi:[1,1,1]
	v_pk_fma_f32 v[60:61], v[100:101], v[158:159], v[60:61] op_sel:[1,0,0] op_sel_hi:[1,1,1]
	s_waitcnt lgkmcnt(8)
	ds_read_b128 v[86:89], v102 offset:544
	ds_read_b128 v[90:93], v102 offset:800
	ds_read_b128 v[94:97], v102 offset:2592
	ds_read_b128 v[98:101], v102 offset:2848
	v_pk_fma_f32 v[46:47], v[108:109], v[240:241], v[46:47] op_sel_hi:[0,1,1]
	v_pk_fma_f32 v[48:49], v[112:113], v[240:241], v[48:49] op_sel_hi:[0,1,1]
	v_pk_fma_f32 v[62:63], v[116:117], v[152:153], v[62:63] op_sel_hi:[0,1,1]
	v_pk_fma_f32 v[64:65], v[120:121], v[152:153], v[64:65] op_sel_hi:[0,1,1]
	v_pk_fma_f32 v[46:47], v[108:109], v[242:243], v[46:47] op_sel:[1,0,0] op_sel_hi:[1,1,1]
	v_pk_fma_f32 v[48:49], v[112:113], v[242:243], v[48:49] op_sel:[1,0,0] op_sel_hi:[1,1,1]
	v_pk_fma_f32 v[62:63], v[116:117], v[154:155], v[62:63] op_sel:[1,0,0] op_sel_hi:[1,1,1]
	v_pk_fma_f32 v[64:65], v[120:121], v[154:155], v[64:65] op_sel:[1,0,0] op_sel_hi:[1,1,1]
	v_pk_fma_f32 v[46:47], v[110:111], v[244:245], v[46:47] op_sel_hi:[0,1,1]
	v_pk_fma_f32 v[48:49], v[114:115], v[244:245], v[48:49] op_sel_hi:[0,1,1]
	v_pk_fma_f32 v[62:63], v[118:119], v[156:157], v[62:63] op_sel_hi:[0,1,1]
	v_pk_fma_f32 v[64:65], v[122:123], v[156:157], v[64:65] op_sel_hi:[0,1,1]
	v_pk_fma_f32 v[46:47], v[110:111], v[246:247], v[46:47] op_sel:[1,0,0] op_sel_hi:[1,1,1]
	v_pk_fma_f32 v[48:49], v[114:115], v[246:247], v[48:49] op_sel:[1,0,0] op_sel_hi:[1,1,1]
	v_pk_fma_f32 v[62:63], v[118:119], v[158:159], v[62:63] op_sel:[1,0,0] op_sel_hi:[1,1,1]
	v_pk_fma_f32 v[64:65], v[122:123], v[158:159], v[64:65] op_sel:[1,0,0] op_sel_hi:[1,1,1]
	s_waitcnt lgkmcnt(8)
	ds_read_b128 v[108:111], v102 offset:1056
	ds_read_b128 v[112:115], v102 offset:1312
	ds_read_b128 v[116:119], v102 offset:3104
	ds_read_b128 v[120:123], v102 offset:3360
	v_pk_fma_f32 v[50:51], v[136:137], v[240:241], v[50:51] op_sel_hi:[0,1,1]
	v_pk_fma_f32 v[52:53], v[140:141], v[240:241], v[52:53] op_sel_hi:[0,1,1]
	v_pk_fma_f32 v[66:67], v[144:145], v[152:153], v[66:67] op_sel_hi:[0,1,1]
	v_pk_fma_f32 v[68:69], v[148:149], v[152:153], v[68:69] op_sel_hi:[0,1,1]
	v_pk_fma_f32 v[50:51], v[136:137], v[242:243], v[50:51] op_sel:[1,0,0] op_sel_hi:[1,1,1]
	v_pk_fma_f32 v[52:53], v[140:141], v[242:243], v[52:53] op_sel:[1,0,0] op_sel_hi:[1,1,1]
	v_pk_fma_f32 v[66:67], v[144:145], v[154:155], v[66:67] op_sel:[1,0,0] op_sel_hi:[1,1,1]
	v_pk_fma_f32 v[68:69], v[148:149], v[154:155], v[68:69] op_sel:[1,0,0] op_sel_hi:[1,1,1]
	v_pk_fma_f32 v[50:51], v[138:139], v[244:245], v[50:51] op_sel_hi:[0,1,1]
	v_pk_fma_f32 v[52:53], v[142:143], v[244:245], v[52:53] op_sel_hi:[0,1,1]
	v_pk_fma_f32 v[66:67], v[146:147], v[156:157], v[66:67] op_sel_hi:[0,1,1]
	v_pk_fma_f32 v[68:69], v[150:151], v[156:157], v[68:69] op_sel_hi:[0,1,1]
	v_pk_fma_f32 v[50:51], v[138:139], v[246:247], v[50:51] op_sel:[1,0,0] op_sel_hi:[1,1,1]
	v_pk_fma_f32 v[52:53], v[142:143], v[246:247], v[52:53] op_sel:[1,0,0] op_sel_hi:[1,1,1]
	v_pk_fma_f32 v[66:67], v[146:147], v[158:159], v[66:67] op_sel:[1,0,0] op_sel_hi:[1,1,1]
	v_pk_fma_f32 v[68:69], v[150:151], v[158:159], v[68:69] op_sel:[1,0,0] op_sel_hi:[1,1,1]
	v_add_u32_e32 v102, 32, v102
	s_add_i32 s14, s14, 1
	s_cmp_lt_u32 s14, 8
	s_cbranch_scc1 .Llora_loop
; DI bf16_t f2bf(float f) { return (bf16_t)(pack2(f, f) & 0xFFFFu); }
; DI void prep_phase(const Params& p, int l, char* smem, const bool dry = false) {
;     ...
;       for (int ch = 0; ch < 2; ch++) {
;         const int c = tid + 256 * ch;
;         const int head = wave + 4 * ch;
;         const float muR = mu[c], muK = mu[512 + c], muV = mu[1024 + c];
;         const float kkc = p.k_k[l * 512 + c], kac = p.k_a[l * 512 + c], rkc = p.r_k[l * 512 + c];
; #pragma unroll
;         for (int tk = 0; tk < 8; tk++) {
;           const float* rc = rows + (tk + 1) * DSH;
;           const float* rp = rows + tk * DSH;
;           const float r = rc[c] + (rp[c] - rc[c]) * muR;
;           const float k = rc[512 + c] + (rp[512 + c] - rc[512 + c]) * muK;
;           const float v = rc[1024 + c] + (rp[1024 + c] - rc[1024 + c]) * muV;
;           const float xw = -accw[ch][tk];
;           const float sp = fmaxf(xw, 0.f) + __logf(1.f + __expf(-fabsf(xw)));
;           const float w = -sp - 0.5f;
;           const float decay = __expf(-__expf(w));
;           const float ag = __builtin_amdgcn_rcpf(1.f + __expf(-acca[ch][tk]));
;           const float kkr = k * kkc;
;           const float ss = wave_sum(kkr * kkr);
;           const float kk = kkr * fminf(__builtin_amdgcn_rsqf(ss), 1e12f);
;           const float kp = k * (1.f + (ag - 1.f) * kac);
;           const float bon = wave_sum(r * kp * rkc);
;           float* Rrow = p.R + (size_t)(tb + tk) * RS;
;           bf16_t* Rb = (bf16_t*)(Rrow + 512);
;           if (!dry) {
;             Rrow[c] = decay;
;             Rb[c] = f2bf(r);
;             Rb[512 + c] = f2bf(kp);
;             Rb[1024 + c] = f2bf(v);
;             Rb[1536 + c] = f2bf(-kk);
;             Rb[2048 + c] = f2bf(kk * ag);
;             if (lane == 0) p.bonus[(size_t)(tb + tk) * 8 + head] = bon;
;           } else if (decay + r + kp + v + kk + bon == 1.2345e30f) p.wi[0] = 1.f;
;         }
;       }
	s_waitcnt lgkmcnt(0)
	v_mov_b32_e32 v70, v38
	v_mov_b32_e32 v71, v39
	v_mov_b32_e32 v72, v54
	v_mov_b32_e32 v73, v55
	v_mov_b32_e32 v74, v40
	v_mov_b32_e32 v75, v41
	v_mov_b32_e32 v76, v56
	v_mov_b32_e32 v77, v57
	v_mov_b32_e32 v78, v42
	v_mov_b32_e32 v79, v43
	v_mov_b32_e32 v80, v58
	v_mov_b32_e32 v81, v59
	v_mov_b32_e32 v82, v44
	v_mov_b32_e32 v83, v45
	v_mov_b32_e32 v84, v60
	v_mov_b32_e32 v85, v61
	v_mov_b32_e32 v86, v46
	v_mov_b32_e32 v87, v47
	v_mov_b32_e32 v88, v62
	v_mov_b32_e32 v89, v63
	v_mov_b32_e32 v90, v48
	v_mov_b32_e32 v91, v49
	v_mov_b32_e32 v92, v64
	v_mov_b32_e32 v93, v65
	v_mov_b32_e32 v94, v50
	v_mov_b32_e32 v95, v51
	v_mov_b32_e32 v96, v66
	v_mov_b32_e32 v97, v67
	v_mov_b32_e32 v98, v52
	v_mov_b32_e32 v99, v53
	v_mov_b32_e32 v100, v68
	v_mov_b32_e32 v101, v69
	v_mov_b32_e32 v68, v70
	v_mov_b32_e32 v69, v74
	v_mov_b32_e32 v64, v78
	v_mov_b32_e32 v65, v82
	v_mov_b32_e32 v60, v86
	v_mov_b32_e32 v61, v90
	v_mov_b32_e32 v56, v94
	v_mov_b32_e32 v57, v98
	v_mov_b32_e32 v66, v72
	v_mov_b32_e32 v67, v76
	v_mov_b32_e32 v62, v80
	v_mov_b32_e32 v63, v84
	v_mov_b32_e32 v58, v88
	v_mov_b32_e32 v59, v92
	v_mov_b32_e32 v54, v96
	v_mov_b32_e32 v55, v100
	v_mov_b32_e32 v52, v71
	v_mov_b32_e32 v53, v75
	v_mov_b32_e32 v48, v79
	v_mov_b32_e32 v49, v83
	v_mov_b32_e32 v44, v87
	v_mov_b32_e32 v45, v91
	v_mov_b32_e32 v40, v95
	v_mov_b32_e32 v41, v99
	v_mov_b32_e32 v50, v73
	v_mov_b32_e32 v51, v77
	v_mov_b32_e32 v46, v81
	v_mov_b32_e32 v47, v85
	v_mov_b32_e32 v42, v89
	v_mov_b32_e32 v43, v93
	v_mov_b32_e32 v38, v97
	v_mov_b32_e32 v39, v101
	global_load_dword v109, v[10:11], off
	global_load_dword v108, v[10:11], off offset:2048
	global_load_dword v102, v[12:13], off
	global_load_dword v105, v[20:21], off
	global_load_dword v103, v[22:23], off
	global_load_dword v104, v[24:25], off
	v_max_f32_e64 v76, -v68, -v68
	v_mul_f32_e64 v68, |v68|, s33
	v_exp_f32_e32 v68, v68
	ds_read2st64_b32 v[74:75], v107 offset0:16 offset1:26
	ds_read2st64_b32 v[70:71], v107 offset1:8
	ds_read2st64_b32 v[72:73], v107 offset0:34 offset1:42
	v_max_f32_e32 v76, 0, v76
	v_add_f32_e32 v68, 1.0, v68
	v_cmp_gt_f32_e32 vcc, s3, v68
	v_mul_f32_e32 v66, 0xbfb8aa3b, v66
	s_waitcnt lgkmcnt(0)
	v_sub_f32_e32 v71, v71, v72
	v_cndmask_b32_e64 v77, 0, 32, vcc
	v_ldexp_f32 v68, v68, v77
	v_log_f32_e32 v68, v68
	v_exp_f32_e32 v66, v66
	v_mov_b32_e32 v78, v164
	v_sub_f32_e32 v70, v70, v75
	v_mul_f32_e32 v77, 0x3f317217, v68
	v_fma_f32 v77, v68, s2, -v77
	v_fmac_f32_e32 v77, 0x3377d1cf, v68
	v_fmac_f32_e32 v77, 0x3f317217, v68
	v_cmp_lt_f32_e64 s[14:15], |v68|, s91
	v_add_f32_e32 v66, 1.0, v66
	v_rcp_f32_e32 v66, v66
	v_cndmask_b32_e64 v68, v68, v77, s[14:15]
	v_cndmask_b32_e32 v77, 0, v202, vcc
	v_sub_f32_e32 v68, v68, v77
	v_add_f32_e32 v68, v76, v68
	v_sub_f32_e32 v68, -0.5, v68
	v_mul_f32_e32 v68, 0x3fb8aa3b, v68
	v_exp_f32_e32 v68, v68
	v_mov_b32_e32 v79, v164
	v_mul_f32_e32 v68, 0xbfb8aa3b, v68
	v_exp_f32_e32 v68, v68
	s_waitcnt vmcnt(5)
	v_fma_f32 v70, v109, v70, v75
	s_waitcnt vmcnt(4)
	v_fma_f32 v71, v108, v71, v72
	s_waitcnt vmcnt(2)
	v_mul_f32_e32 v76, v105, v71
	v_mul_f32_e32 v77, v76, v76
	s_nop 1
	v_mov_b32_dpp v78, v77 quad_perm:[1,0,3,2] row_mask:0xf bank_mask:0xf
	v_fmac_f32_e32 v78, v76, v76
	s_nop 1
	v_add_f32_dpp v77, v78, v78 quad_perm:[2,3,0,1] row_mask:0xf bank_mask:0xf bound_ctrl:1
	s_nop 1
	v_add_f32_dpp v77, v77, v77 row_half_mirror row_mask:0xf bank_mask:0xf bound_ctrl:1
	s_nop 1
	v_add_f32_dpp v77, v77, v77 row_mirror row_mask:0xf bank_mask:0xf bound_ctrl:1
	s_nop 0
	v_readlane_b32 s15, v77, 16
	v_readlane_b32 s22, v77, 48
	v_readlane_b32 s14, v77, 0
	v_readlane_b32 s21, v77, 32
	v_mov_b32_e32 v77, s15
	v_mov_b32_e32 v78, s22
	v_add_f32_e32 v77, s14, v77
	v_add_f32_e32 v78, s21, v78
	v_add_f32_e32 v77, v77, v78
	v_add_f32_e32 v78, -1.0, v66
	s_waitcnt vmcnt(1)
	v_fma_f32 v78, v78, v103, 1.0
	v_mul_f32_e32 v80, v78, v71
	v_mul_f32_e32 v71, v70, v80
	s_waitcnt vmcnt(0)
	v_mul_f32_e32 v78, v104, v71
	v_rsq_f32_e32 v77, v77
	v_mad_i64_i32 v[100:101], s[22:23], s20, v203, v[34:35]
	v_mov_b32_dpp v79, v78 quad_perm:[1,0,3,2] row_mask:0xf bank_mask:0xf
	v_fmac_f32_e32 v79, v104, v71
	global_store_dword v[100:101], v68, off
	v_cvt_pk_bf16_f32 v68, v70, s0
	v_add_f32_dpp v71, v79, v79 quad_perm:[2,3,0,1] row_mask:0xf bank_mask:0xf bound_ctrl:1
	v_min_f32_e32 v77, 0x5368d4a5, v77
	v_mul_f32_e32 v76, v76, v77
	v_add_f32_dpp v71, v71, v71 row_half_mirror row_mask:0xf bank_mask:0xf bound_ctrl:1
	v_mul_f32_e32 v66, v66, v76
	s_ashr_i32 s21, s20, 31
	v_add_f32_dpp v71, v71, v71 row_mirror row_mask:0xf bank_mask:0xf bound_ctrl:1
	v_cvt_pk_bf16_f32 v66, v66, s0
	v_readlane_b32 s14, v71, 0
	v_readlane_b32 s26, v71, 16
	v_readlane_b32 s15, v71, 32
	v_readlane_b32 s27, v71, 48
	v_sub_f32_e32 v71, v74, v73
	v_fma_f32 v74, v102, v71, v73
	v_lshl_add_u64 v[70:71], v[100:101], 0, v[36:37]
	global_store_short v[70:71], v68, off offset:2048
	v_cvt_pk_bf16_f32 v68, v80, s0
	v_lshl_add_u64 v[78:79], v[70:71], 0, s[62:63]
	global_store_short v[70:71], v68, off offset:3072
	v_cvt_pk_bf16_f32 v68, v74, s0
	global_store_short v[78:79], v68, off offset:2048
	v_cvt_pk_bf16_f32 v68, -v76, s0
	v_add_co_u32_e32 v76, vcc, 0x1000, v70
	global_store_short v[78:79], v68, off offset:3072
	s_nop 0
	v_addc_co_u32_e32 v77, vcc, 0, v71, vcc
	global_store_short v[76:77], v66, off offset:2048
	s_and_saveexec_b64 s[22:23], s[10:11]
	s_cbranch_execz .LBB0_1179
	v_mov_b32_e32 v76, s26
	v_mov_b32_e32 v77, s27
	s_lshl_b64 s[28:29], s[20:21], 5
	v_pk_add_f32 v[76:77], s[14:15], v[76:77]
	s_nop 0
	v_add_f32_e32 v66, v76, v77
	v_lshl_add_u64 v[76:77], v[26:27], 0, s[28:29]
	global_store_dword v[76:77], v66, off
